# v28: SWA bias-table loads batched, P6 span prologue loads merged into one round trip, P10 final gain loads hoisted above rstd exchange
# baseline (speedup 1.0000x reference)
; #define LAS __attribute__((address_space(3)))
; template <class T> __device__ __forceinline__ LAS T* opq(LAS T* p) { unsigned a = __builtin_bit_cast(unsigned, p); asm volatile("" : "+v"(a)); return __builtin_bit_cast(LAS T*, a); }
; __device__ __forceinline__ void phase(LAS unsigned char* lds, int bx, int G, bf16_t* AB, bf16_t* dummy, const bf16_t* SKV, const float* cache_k, const float* cache_v, const float* sinks, const float* rel_bias) {
;     ...
;         const bool samp = t.samp; const int b = t.b, kh = t.kh, c = t.c, kvmin = t.kvmin, kvmax = t.kvmax;
;         {
;             LAS bf16_t* kwp = opq(Ks + (tid >> 3) * KST + (tid & 7) * 8); LAS bf16_t* vwp = opq(Vs + (tid >> 3) * VSS + (tid & 7) * 8);
; #pragma unroll
;             for (int i = 0; i < 3; ++i) { const int kv = (tid >> 3) + 64 * i; const bool ok = kv >= kvmin && kv < kvmax; const u32x4 z4 = (u32x4){0u, 0u, 0u, 0u};
;                 *(LAS u32x4*)(kwp + 64 * i * KST) = ok ? kw[i] : z4; *(LAS u32x4*)(vwp + 64 * i * VSS) = ok ? vw[i] : z4; }
;             if (kh != cur_kh) {
;                 LAS float* twp = opq(tbl + tid);
; #pragma unroll
;                 for (int i = 0; i < 2; ++i) { const int idx = tid + 512 * i, g = idx >> 8, ii = idx & 255; twp[512 * i] = ii == 255 ? LOG2E * sinks[4 * kh + g] : LOG2E * rel_bias[t5_bucket(ii - 191) * 16 + 4 * kh + g]; }
;                 cur_kh = kh;
;             }
.LBB0_1147:
	s_cmp_gt_u32 s28, 1
	s_cselect_b64 s[6:7], -1, 0
	s_lshl_b32 s31, s28, 6
	s_or_b64 s[6:7], s[4:5], s[6:7]
	s_sub_i32 s26, 0x80, s31
	s_and_b64 s[6:7], s[6:7], exec
	s_cselect_b32 s35, 0, s26
	v_cmp_gt_u32_e32 vcc, s35, v174
	v_mov_b32_e32 v10, v177
	v_cmp_gt_u32_e64 s[6:7], s34, v175
	v_cndmask_b32_e64 v5, v101, 0, vcc
	v_cndmask_b32_e64 v4, v100, 0, vcc
	v_cndmask_b32_e64 v3, v99, 0, vcc
	v_cndmask_b32_e64 v2, v98, 0, vcc
	v_cndmask_b32_e64 v9, v105, 0, vcc
	v_cndmask_b32_e64 v8, v104, 0, vcc
	v_cndmask_b32_e64 v7, v103, 0, vcc
	v_cndmask_b32_e64 v6, v102, 0, vcc
	v_cmp_le_u32_e32 vcc, s35, v175
	v_mov_b32_e32 v11, v178
	s_and_b64 vcc, vcc, s[6:7]
	ds_write_b128 v10, v[2:5]
	ds_write_b128 v11, v[6:9]
	v_cndmask_b32_e32 v5, 0, v109, vcc
	v_cndmask_b32_e32 v4, 0, v108, vcc
	v_cndmask_b32_e32 v3, 0, v107, vcc
	v_cndmask_b32_e32 v2, 0, v106, vcc
	v_cndmask_b32_e32 v9, 0, v113, vcc
	v_cndmask_b32_e32 v8, 0, v112, vcc
	v_cndmask_b32_e32 v7, 0, v111, vcc
	v_cndmask_b32_e32 v6, 0, v110, vcc
	v_cmp_gt_u32_e32 vcc, s34, v176
	s_and_b32 s55, s27, 3
	ds_write_b128 v10, v[2:5] offset:9216
	ds_write_b128 v11, v[6:9] offset:12288
	v_cndmask_b32_e32 v5, 0, v117, vcc
	v_cndmask_b32_e32 v4, 0, v116, vcc
	v_cndmask_b32_e32 v3, 0, v115, vcc
	v_cndmask_b32_e32 v2, 0, v114, vcc
	v_cndmask_b32_e32 v9, 0, v121, vcc
	v_cndmask_b32_e32 v8, 0, v120, vcc
	v_cndmask_b32_e32 v7, 0, v119, vcc
	v_cndmask_b32_e32 v6, 0, v118, vcc
	s_cmp_eq_u32 s55, s53
	ds_write_b128 v10, v[2:5] offset:18432
	ds_write_b128 v11, v[6:9] offset:24576
	s_cbranch_scc1 .LBB0_1157
	v_mov_b32_e32 v4, v179
	s_lshl_b32 s26, s55, 2
	s_and_saveexec_b64 s[6:7], s[16:17]
	s_xor_b64 s[6:7], exec, s[6:7]
	v_or_b32_e32 v2, s26, v187
	v_ashrrev_i32_e32 v3, 31, v2
	v_lshl_add_u64 v[2:3], v[2:3], 2, s[36:37]
	s_andn2_saveexec_b64 s[6:7], s[6:7]
	v_or_b32_e32 v2, s26, v199
	v_lshlrev_b32_e32 v2, 2, v2
	v_mov_b32_e32 v3, v155
	v_lshl_add_u64 v[2:3], s[66:67], 0, v[2:3]
	s_or_b64 exec, exec, s[6:7]
	global_load_dword v254, v[2:3], off
	s_and_saveexec_b64 s[6:7], s[16:17]
	s_xor_b64 s[6:7], exec, s[6:7]
	v_add_u32_e32 v2, s26, v189
	v_ashrrev_i32_e32 v3, 31, v2
	v_lshl_add_u64 v[2:3], v[2:3], 2, s[36:37]
	s_andn2_saveexec_b64 s[6:7], s[6:7]
	v_add_lshl_u32 v2, s26, v188, 2
	v_mov_b32_e32 v3, v155
	v_lshl_add_u64 v[2:3], s[66:67], 0, v[2:3]
	s_or_b64 exec, exec, s[6:7]
	global_load_dword v2, v[2:3], off
	s_mov_b32 s53, s55
	s_waitcnt vmcnt(1)
	v_mul_f32_e32 v254, 0x3fb8aa3b, v254
	ds_write_b32 v4, v254
	s_waitcnt vmcnt(0)
	v_mul_f32_e32 v2, 0x3fb8aa3b, v2
	ds_write_b32 v4, v2 offset:2048

; #define LAS __attribute__((address_space(3)))
; template <bool FULL, bool PARTIAL  > ...
;     ...
;     float wal[8];
; #pragma unroll
;     for (int i = 0; i < 8; ++i) wal[i] = w_alpha[(2 * i + h) * 512 + hd * 128 + kk];
;     const float bal = b_alpha[hd * 128 + kk];
;     f32x16 Sacc[4];
;     float dsum = 0.f;
;     if (FULL && tid < 256) ((LAS float*)(lds + OFF_HN))[tid] = head_norm[tid];
;     f32x4 raw_ga; u32x4 raw_k[2], raw_q[2];
;     const int nv1 = nvalid - 1;
;     const u32x4 z4 = (u32x4){0u, 0u, 0u, 0u};
;     ...
;     GLA_FETCH_KG(0);
;     asm volatile("" :: "v"(raw_ga), "v"(raw_k[0]), "v"(raw_k[1]));
;     if (FULL) asm volatile("" :: "v"(raw_q[0]), "v"(raw_q[1]));
;     if (FULL && S0) {
;         const float* s0p = S0 + (size_t)(4 * h) * 256 + 32 * w + r;
; #pragma unroll
;         for (int kb = 0; kb < 4; ++kb)
; #pragma unroll
;             for (int i = 0; i < 16; ++i) Sacc[kb][i] = s0p[(32 * kb + (i & 3) + 8 * (i >> 2)) * 256];
.LBB0_1305:
	v_readfirstlane_b32 s10, v0
	s_lshr_b32 s11, s10, 6
	s_lshl_b32 s60, s11, 5
	s_and_b32 s12, s62, 3
	s_and_b32 s8, s60, 0x60
	v_or_b32_e32 v83, s8, v162
	s_lshl_b32 s13, s12, 7
	v_or3_b32 v2, s13, v163, v83
	v_lshlrev_b32_e32 v2, 2, v2
	v_lshl_add_u64 v[4:5], s[56:57], 0, v[2:3]
	v_add_co_u32_e32 v6, vcc, 0x1000, v4
	global_load_dword v232, v2, s[56:57]
	s_nop 0
	v_addc_co_u32_e32 v7, vcc, 0, v5, vcc
	v_add_co_u32_e32 v8, vcc, 0x2000, v4
	v_or_b32_e32 v2, s13, v83
	s_nop 0
	v_addc_co_u32_e32 v9, vcc, 0, v5, vcc
	v_add_co_u32_e32 v10, vcc, 0x3000, v4
	v_lshlrev_b32_e32 v2, 2, v2
	s_nop 0
	v_addc_co_u32_e32 v11, vcc, 0, v5, vcc
	v_add_co_u32_e32 v12, vcc, 0x4000, v4
	s_nop 1
	v_addc_co_u32_e32 v13, vcc, 0, v5, vcc
	v_add_co_u32_e32 v14, vcc, 0x5000, v4
	s_nop 1
	v_addc_co_u32_e32 v15, vcc, 0, v5, vcc
	v_add_co_u32_e32 v16, vcc, 0x6000, v4
	s_nop 1
	v_addc_co_u32_e32 v17, vcc, 0, v5, vcc
	v_add_co_u32_e32 v4, vcc, 0x7000, v4
	s_nop 1
	v_addc_co_u32_e32 v5, vcc, 0, v5, vcc
	global_load_dword v233, v[6:7], off
	global_load_dword v234, v[8:9], off
	global_load_dword v235, v[10:11], off
	global_load_dword v236, v[12:13], off
	global_load_dword v237, v[14:15], off
	global_load_dword v238, v[16:17], off
	global_load_dword v239, v[4:5], off
	global_load_dword v82, v2, s[58:59]
	s_and_saveexec_b64 s[8:9], s[0:1]
	s_cbranch_execz .LBB0_1307
	global_load_dword v254, v[164:165], off
.LBB0_1307:
	s_or_b64 exec, exec, s[8:9]
	s_lshl_b32 s8, s79, 6
	s_and_b32 s8, s8, 0xfffff000
	s_lshl_b32 s9, s63, 8
	s_or_b32 s52, s8, s9
	s_ashr_i32 s53, s52, 31
	v_mov_b32_e32 v6, v0
	s_lshl_b64 s[8:9], s[52:53], 6
	s_add_u32 s14, s96, s8
	v_ashrrev_i32_e32 v2, 2, v6
	v_lshlrev_b32_e32 v4, 2, v6
	s_addc_u32 s15, s97, s9
	s_lshl_b64 s[8:9], s[52:53], 11
	v_min_i32_e32 v2, 63, v2
	v_and_b32_e32 v4, 12, v4
	s_add_u32 s16, s40, s8
	v_lshl_or_b32 v2, v2, 4, v4
	s_addc_u32 s9, s41, s9
	s_lshl_b32 s8, s13, 1
	v_lshl_add_u64 v[4:5], v[2:3], 2, s[14:15]
	v_ashrrev_i32_e32 v8, 4, v6
	v_lshlrev_b32_e32 v2, 3, v6
	s_add_u32 s16, s16, s8
	v_and_b32_e32 v9, 0x78, v2
	v_min_i32_e32 v2, 63, v8
	s_addc_u32 s17, s9, 0
	v_lshl_or_b32 v2, v2, 10, v9
	v_lshl_add_u64 v[6:7], v[2:3], 1, s[16:17]
	v_min_i32_e32 v2, 31, v8
	v_lshl_or_b32 v2, v2, 10, v9
	v_add_u32_e32 v2, 0x8000, v2
	global_load_dwordx4 v[130:133], v[4:5], off
	global_load_dwordx4 v[134:137], v[6:7], off
	v_lshl_add_u64 v[4:5], v[2:3], 1, s[16:17]
	global_load_dwordx4 v[138:141], v[4:5], off offset:1024
	global_load_dwordx4 v[142:145], v[6:7], off offset:1024
	global_load_dwordx4 v[146:149], v[4:5], off
	s_cmp_lg_u64 s[6:7], 0
	s_cbranch_scc0 .LBB0_1330
	v_mov_b32_e32 v171, v3
	v_lshl_add_u64 v[4:5], s[6:7], 0, v[170:171]
	v_lshl_add_u64 v[4:5], s[60:61], 2, v[4:5]
	v_mov_b32_e32 v175, v3
	v_lshl_add_u64 v[4:5], v[4:5], 0, v[174:175]
	v_add_co_u32_e32 v6, vcc, 0x2000, v4
	s_nop 1
	v_addc_co_u32_e32 v7, vcc, 0, v5, vcc
	global_load_dword v18, v[4:5], off
	global_load_dword v19, v[4:5], off offset:1024
	global_load_dword v20, v[4:5], off offset:2048
	global_load_dword v21, v[4:5], off offset:3072
	global_load_dword v22, v[6:7], off
	global_load_dword v23, v[6:7], off offset:1024
	global_load_dword v24, v[6:7], off offset:2048
	global_load_dword v25, v[6:7], off offset:3072
	v_add_co_u32_e32 v6, vcc, 0x4000, v4
	s_nop 1
	v_addc_co_u32_e32 v7, vcc, 0, v5, vcc
	v_add_co_u32_e32 v8, vcc, 0x6000, v4
	s_nop 1
	v_addc_co_u32_e32 v9, vcc, 0, v5, vcc
	global_load_dword v26, v[6:7], off
	global_load_dword v27, v[6:7], off offset:1024
	global_load_dword v28, v[6:7], off offset:2048
	global_load_dword v29, v[6:7], off offset:3072
	global_load_dword v30, v[8:9], off
	global_load_dword v31, v[8:9], off offset:1024
	global_load_dword v32, v[8:9], off offset:2048
	global_load_dword v33, v[8:9], off offset:3072
	v_add_co_u32_e32 v6, vcc, 0x8000, v4
	s_nop 1
	v_addc_co_u32_e32 v7, vcc, 0, v5, vcc
	v_add_co_u32_e32 v8, vcc, 0xa000, v4
	s_nop 1
	v_addc_co_u32_e32 v9, vcc, 0, v5, vcc
	global_load_dword v34, v[6:7], off
	global_load_dword v35, v[6:7], off offset:1024
	global_load_dword v36, v[6:7], off offset:2048
	global_load_dword v37, v[6:7], off offset:3072
	global_load_dword v38, v[8:9], off
	global_load_dword v39, v[8:9], off offset:1024
	global_load_dword v40, v[8:9], off offset:2048
	global_load_dword v41, v[8:9], off offset:3072
	v_add_co_u32_e32 v6, vcc, 0xc000, v4
	s_nop 1
	v_addc_co_u32_e32 v7, vcc, 0, v5, vcc
	v_add_co_u32_e32 v8, vcc, 0xe000, v4
	s_nop 1
	v_addc_co_u32_e32 v9, vcc, 0, v5, vcc
	global_load_dword v42, v[6:7], off
	global_load_dword v43, v[6:7], off offset:1024
	global_load_dword v44, v[6:7], off offset:2048
	global_load_dword v45, v[6:7], off offset:3072
	global_load_dword v46, v[8:9], off
	global_load_dword v47, v[8:9], off offset:1024
	global_load_dword v48, v[8:9], off offset:2048
	global_load_dword v49, v[8:9], off offset:3072
	v_add_co_u32_e32 v6, vcc, 0x10000, v4
	s_nop 1
	v_addc_co_u32_e32 v7, vcc, 0, v5, vcc
	v_add_co_u32_e32 v8, vcc, 0x12000, v4
	s_nop 1
	v_addc_co_u32_e32 v9, vcc, 0, v5, vcc
	global_load_dword v50, v[6:7], off
	global_load_dword v51, v[6:7], off offset:1024
	global_load_dword v52, v[6:7], off offset:2048
	global_load_dword v53, v[6:7], off offset:3072
	global_load_dword v54, v[8:9], off
	global_load_dword v55, v[8:9], off offset:1024
	global_load_dword v56, v[8:9], off offset:2048
	global_load_dword v57, v[8:9], off offset:3072
	v_add_co_u32_e32 v6, vcc, 0x14000, v4
	s_nop 1
	v_addc_co_u32_e32 v7, vcc, 0, v5, vcc
	v_add_co_u32_e32 v8, vcc, 0x16000, v4
	s_nop 1
	v_addc_co_u32_e32 v9, vcc, 0, v5, vcc
	global_load_dword v58, v[6:7], off
	global_load_dword v59, v[6:7], off offset:1024
	global_load_dword v60, v[6:7], off offset:2048
	global_load_dword v61, v[6:7], off offset:3072
	global_load_dword v62, v[8:9], off
	global_load_dword v63, v[8:9], off offset:1024
	global_load_dword v64, v[8:9], off offset:2048
	global_load_dword v65, v[8:9], off offset:3072
	v_add_co_u32_e32 v6, vcc, 0x18000, v4
	s_nop 1
	v_addc_co_u32_e32 v7, vcc, 0, v5, vcc
	v_add_co_u32_e32 v8, vcc, 0x1a000, v4
	s_nop 1
	v_addc_co_u32_e32 v9, vcc, 0, v5, vcc
	global_load_dword v66, v[6:7], off
	global_load_dword v67, v[6:7], off offset:1024
	global_load_dword v68, v[6:7], off offset:2048
	global_load_dword v69, v[6:7], off offset:3072
	global_load_dword v70, v[8:9], off
	global_load_dword v71, v[8:9], off offset:1024
	global_load_dword v72, v[8:9], off offset:2048
	global_load_dword v73, v[8:9], off offset:3072
	v_add_co_u32_e32 v6, vcc, 0x1c000, v4
	s_nop 1
	v_addc_co_u32_e32 v7, vcc, 0, v5, vcc
	v_add_co_u32_e32 v4, vcc, 0x1e000, v4
	s_nop 1
	v_addc_co_u32_e32 v5, vcc, 0, v5, vcc
	global_load_dword v74, v[6:7], off
	global_load_dword v75, v[6:7], off offset:1024
	global_load_dword v76, v[6:7], off offset:2048
	global_load_dword v77, v[6:7], off offset:3072
	global_load_dword v78, v[4:5], off
	global_load_dword v79, v[4:5], off offset:1024
	global_load_dword v80, v[4:5], off offset:2048
	global_load_dword v81, v[4:5], off offset:3072
	s_mov_b64 s[64:65], s[60:61]
	s_cbranch_execnz .LBB0_1310

; #define LAS __attribute__((address_space(3)))
; template <class T> __device__ __forceinline__ LAS T* opq(LAS T* p) { unsigned a = __builtin_bit_cast(unsigned, p); asm volatile("" : "+v"(a)); return __builtin_bit_cast(LAS T*, a); }
; template <bool FULL, bool PARTIAL  > ...
;     ...
;     if (FULL && tid < 256) ((LAS float*)(lds + OFF_HN))[tid] = head_norm[tid];
;     ...
;     f32x16 oT[2]; u32x2 grv[2][4];
;     const LAS float* hn_r = opq((LAS float*)(lds + OFF_HN) + 32 * w + 4 * h);
;     LAS float* part_p = opq(PART + r);
;     ...
;     for (int c = 0; c < nch; ++c) {
;         const int crow0 = row0 + 64 * c;
;         if (tid < 256) { LAS float* gp_ = GAs + ((tid & 3) * 4) * 68 + (tid >> 2); gp_[0] = raw_ga[0]; gp_[68] = raw_ga[1]; gp_[136] = raw_ga[2]; gp_[204] = raw_ga[3]; }
;         {
;             LAS bf16_t* ks_st = opq(KS + (tid >> 4) * QST + (tid & 15) * 8);
; #pragma unroll
;             for (int i = 0; i < 2; ++i) { *(LAS u32x4*)(ks_st + 32 * i * QST) = raw_k[i]; if (FULL) *(LAS u32x4*)(ks_st - 64 * QST + 32 * i * QST) = raw_q[i]; }
;         }
;         u32x4 raw_v[4];
;         GLA_FETCH_QV(c);
;         __syncthreads();
;         if (FULL && c > 0) GLA_S6(crow0 - 64);
;         float bc[16];
;         {
;             f32x16 bacc;
; #pragma unroll
;             for (int i = 0; i < 16; ++i) bacc[i] = bal;
;             const LAS float* ga_r = opq(GAs + h * 68 + 32 * tt + r);
.LBB0_1310:
	s_waitcnt vmcnt(63)
	s_and_saveexec_b64 s[100:101], s[0:1]
	ds_write_b32 v216, v254
	s_mov_b64 exec, s[100:101]
	s_and_b32 s7, s78, 15
	s_and_b32 s6, s89, 0xfffff000
	s_lshl_b32 s7, s7, 8
	s_or_b32 s54, s6, s7
	s_ashr_i32 s55, s54, 31
	s_lshr_b32 s9, s10, 8
	s_lshl_b64 s[74:75], s[54:55], 12
	s_lshl_b64 s[6:7], s[54:55], 11
	s_add_u32 s53, s80, s6
	s_addc_u32 s55, s81, s7
	s_add_u32 s82, s40, s8
	s_addc_u32 s83, s41, 0
	s_lshl_b32 s6, s12, 9
	s_add_u32 s6, s92, s6
	s_addc_u32 s7, s93, 0
	s_lshl_b32 s72, s64, 1
	s_add_u32 s6, s6, s72
	v_lshlrev_b32_e32 v4, 2, v83
	s_addc_u32 s7, s7, 0
	s_lshl_b32 s90, s9, 9
	v_add_u32_e32 v240, s43, v4
	v_lshl_add_u32 v2, v83, 1, 0
	v_mov_b32_e32 v173, v3
	s_cmpk_lt_u32 s10, 0x100
	v_add_u32_e32 v241, s88, v4
	v_lshl_or_b32 v4, s9, 5, v217
	v_lshl_add_u64 v[16:17], s[6:7], 0, v[172:173]
	s_cselect_b64 s[66:67], -1, 0
	v_mad_u64_u32 v[176:177], s[6:7], v4, s86, v[2:3]
	s_and_b64 s[76:77], s[4:5], s[66:67]
	s_lshl_b32 s6, s9, 6
	v_mul_u32_u24_e32 v4, 0x8e, v83
	s_cmpk_lt_u32 s10, 0xc0
	v_add3_u32 v2, v2, v4, s6
	v_lshlrev_b32_e32 v4, 1, v217
	s_mov_b32 s6, 0x8800
	s_cselect_b64 s[84:85], -1, 0
	s_cmp_gt_u32 s10, 63
	v_add3_u32 v177, v2, v4, s6
	s_cselect_b32 s6, 32, 0
	s_cmp_eq_u32 s11, 2
	v_or_b32_e32 v2, s6, v162
	s_cselect_b32 s7, 32, 0
	v_mad_u32_u24 v242, v2, s86, v224
	v_or_b32_e32 v2, s7, v162
	v_mul_u32_u24_e32 v4, 0x110, v2
	v_add3_u32 v243, v224, v4, s87
	v_or_b32_e32 v4, s6, v217
	s_lshl_b32 s6, s7, 1
	s_add_i32 s6, s6, 0
	v_mov_b32_e32 v5, s6
	s_movk_i32 s6, 0x90
	v_lshl_add_u32 v171, s60, 2, v218
	v_mad_u32_u24 v5, v4, s6, v5
	v_lshlrev_b32_e32 v6, 1, v162
	s_mov_b32 s6, 0xd000
	v_sub_u32_e32 v2, v2, v4
	v_lshl_add_u32 v4, s60, 1, v226
	s_lshl_b32 s60, s79, 5
	v_add3_u32 v244, v5, v6, s6
	s_and_b32 s6, s10, 0x3fffffc0
	s_and_b32 s60, s60, 0x600
	s_add_u32 s72, s74, s72
	v_mov_b32_e32 v175, v219
	s_addc_u32 s73, s75, 0
	v_lshl_add_u32 v173, s9, 7, v222
	s_mov_b32 s91, 0
	v_add_u32_e32 v245, 0xf400, v4
	v_lshl_add_u32 v246, s6, 2, v175
	v_mov_b32_e32 v83, v82
	v_mov_b32_e32 v84, v82
	v_mov_b32_e32 v85, v82
	v_mov_b32_e32 v86, v82
	v_mov_b32_e32 v87, v82
	v_mov_b32_e32 v88, v82
	v_mov_b32_e32 v89, v82
	v_mov_b32_e32 v90, v82
	v_mov_b32_e32 v91, v82
	v_mov_b32_e32 v92, v82
	v_mov_b32_e32 v93, v82
	v_mov_b32_e32 v94, v82
	v_mov_b32_e32 v95, v82
	v_mov_b32_e32 v96, v82
	v_mov_b32_e32 v97, v82
	v_cmp_lt_i32_e64 s[6:7], 0, v2
	v_cmp_lt_i32_e64 s[8:9], 1, v2
	v_cmp_lt_i32_e64 s[10:11], 2, v2
	v_cmp_lt_i32_e64 s[12:13], 3, v2
	v_cmp_lt_i32_e64 s[14:15], 8, v2
	v_cmp_lt_i32_e64 s[16:17], 9, v2
	v_cmp_lt_i32_e64 s[18:19], 10, v2
	v_cmp_lt_i32_e64 s[20:21], 11, v2
	v_cmp_lt_i32_e64 s[22:23], 16, v2
	v_cmp_lt_i32_e64 s[24:25], 17, v2
	v_cmp_lt_i32_e64 s[26:27], 18, v2
	v_cmp_lt_i32_e64 s[28:29], 19, v2
	v_cmp_lt_i32_e64 s[30:31], 24, v2
	v_cmp_lt_i32_e64 s[34:35], 25, v2
	v_cmp_lt_i32_e64 s[36:37], 26, v2
	v_cmp_lt_i32_e64 s[38:39], 27, v2
	v_lshl_add_u64 v[178:179], v[168:169], 0, s[72:73]
	s_branch .LBB0_1312

; #define LAS __attribute__((address_space(3)))
;     __device__ __forceinline__ void fused(Acc& acc, const Unit& u, int wr, int wc, int fr, int fq, LAS unsigned char* lds) const {
;     ...
;         __syncthreads();
;         float mine = 0.f;
;         if (threadIdx.x < 256) { const f32x4 p = *(const LAS f32x4*)(Pw + threadIdx.x * 4); mine = (p[0] + p[1]) + (p[2] + p[3]); }
;         xchg_rstd(mine, S, 256, slots + (size_t)u.pm * BM * 16, u.pn, 4, cnt + 64 * u.pm, 4u);
;         f32x4 gg[2][2];
; #pragma unroll
;         for (int bj = 0; bj < 2; ++bj) { const int col = u.pn * BM + bj * HALF + wc * 32 + 8 * fq; gg[bj][0] = *(const f32x4*)(gain + col); gg[bj][1] = *(const f32x4*)(gain + col + 4); }
.LBB0_1910:
	s_or_b64 exec, exec, s[0:1]
	v_or_b32_e32 v254, s22, v164
	v_or_b32_e32 v254, s2, v254
	v_ashrrev_i32_e32 v255, 31, v254
	v_lshlrev_b64 v[254:255], 2, v[254:255]
	v_lshl_add_u64 v[254:255], s[48:49], 0, v[254:255]
	global_load_dwordx4 v[212:215], v[254:255], off
	global_load_dwordx4 v[208:211], v[254:255], off offset:16
	global_load_dwordx4 v[204:207], v[254:255], off offset:512
	global_load_dwordx4 v[200:203], v[254:255], off offset:528
	s_movk_i32 s0, 0x100
	v_cmp_gt_u32_e64 s[0:1], s0, v0
	v_mov_b32_e32 v4, 0
	s_waitcnt lgkmcnt(0)
	s_barrier
	s_and_saveexec_b64 s[6:7], s[0:1]
	s_cbranch_execz .LBB0_1912
	v_add_u32_e32 v2, 0, v130
	ds_read_b128 v[2:5], v2
	s_waitcnt lgkmcnt(0)
	v_mov_b32_e32 v6, v3
	v_mov_b32_e32 v7, v4
	v_mov_b32_e32 v3, v5
	v_pk_add_f32 v[2:3], v[6:7], v[2:3]
	s_nop 0
	v_pk_add_f32 v[4:5], v[2:3], v[2:3] op_sel:[0,1] op_sel_hi:[1,0]

;     __device__ __forceinline__ void fused(Acc& acc, const Unit& u, int wr, int wc, int fr, int fq, LAS unsigned char* lds) const {
;     ...
; #pragma unroll
;         for (int ai = 0; ai < 2; ++ai)
; #pragma unroll
;             for (int m = 0; m < 4; ++m) {
;                 const int rt = ai * HALF + wr * 64 + m * 16 + fr; const int row = u.pm * BM + rt; const float rs = S[rt];
; #pragma unroll
;                 for (int bj = 0; bj < 2; ++bj) {
;                     const int col = u.pn * BM + bj * HALF + wc * 32 + 8 * fq; const size_t off = (size_t)row * D + col;
;                     *(f32x4*)(out + off) = acc[ai][bj][m][0] * rs * gg[bj][0]; *(f32x4*)(out + off + 4) = acc[ai][bj][m][1] * rs * gg[bj][1];
;                 }
;             }
.LBB0_1929:
	s_or_b64 exec, exec, s[8:9]
	v_or_b32_e32 v2, s22, v164
	v_or_b32_e32 v2, s2, v2
	v_ashrrev_i32_e32 v3, 31, v2
	v_lshlrev_b64 v[164:165], 2, v[2:3]
	v_lshl_add_u64 v[2:3], s[48:49], 0, v[164:165]
	s_waitcnt lgkmcnt(0)
	s_barrier
	v_lshl_add_u32 v167, v167, 2, 0
	v_add_u32_e32 v167, 0x1000, v167
	ds_read2_b32 v[168:169], v167 offset1:16
	ds_read2_b32 v[170:171], v167 offset0:32 offset1:48
	v_lshlrev_b64 v[134:135], 12, v[134:135]
	v_lshlrev_b64 v[136:137], 12, v[136:137]
	v_lshl_add_u64 v[134:135], s[50:51], 0, v[134:135]
	v_lshl_add_u64 v[136:137], s[50:51], 0, v[136:137]
	v_lshlrev_b64 v[138:139], 12, v[138:139]
	v_lshl_add_u64 v[172:173], v[134:135], 0, v[164:165]
	v_lshl_add_u64 v[174:175], v[136:137], 0, v[164:165]
	s_waitcnt lgkmcnt(1)
	v_pk_mul_f32 v[128:129], v[128:129], v[168:169] op_sel_hi:[1,0]
	v_pk_mul_f32 v[126:127], v[126:127], v[168:169] op_sel_hi:[1,0]
	v_pk_mul_f32 v[124:125], v[124:125], v[168:169] op_sel_hi:[1,0]
	v_pk_mul_f32 v[122:123], v[122:123], v[168:169] op_sel_hi:[1,0]
	v_pk_mul_f32 v[120:121], v[120:121], v[168:169] op_sel_hi:[1,0]
	v_pk_mul_f32 v[118:119], v[118:119], v[168:169] op_sel_hi:[1,0]
	v_pk_mul_f32 v[116:117], v[116:117], v[168:169] op_sel_hi:[1,0]
	v_pk_mul_f32 v[114:115], v[114:115], v[168:169] op_sel_hi:[1,0]
	v_mov_b32_e32 v134, v169
	s_waitcnt lgkmcnt(0)
	v_pk_mul_f32 v[136:137], v[96:97], v[170:171] op_sel_hi:[1,0]
	v_pk_mul_f32 v[140:141], v[140:141], v[170:171] op_sel_hi:[1,0]
	v_pk_mul_f32 v[168:169], v[92:93], v[170:171] op_sel_hi:[1,0]
	v_pk_mul_f32 v[176:177], v[94:95], v[170:171] op_sel_hi:[1,0]
	v_pk_mul_f32 v[178:179], v[88:89], v[170:171] op_sel_hi:[1,0]
	v_pk_mul_f32 v[180:181], v[90:91], v[170:171] op_sel_hi:[1,0]
	v_pk_mul_f32 v[182:183], v[84:85], v[170:171] op_sel_hi:[1,0]
	v_pk_mul_f32 v[184:185], v[86:87], v[170:171] op_sel_hi:[1,0]
	v_mov_b32_e32 v170, v171
	v_lshlrev_b64 v[82:83], 12, v[82:83]
	v_lshl_add_u64 v[138:139], s[50:51], 0, v[138:139]
	v_pk_mul_f32 v[112:113], v[112:113], v[134:135] op_sel_hi:[1,0]
	v_pk_mul_f32 v[110:111], v[110:111], v[134:135] op_sel_hi:[1,0]
	v_pk_mul_f32 v[108:109], v[108:109], v[134:135] op_sel_hi:[1,0]
	v_pk_mul_f32 v[106:107], v[106:107], v[134:135] op_sel_hi:[1,0]
	v_pk_mul_f32 v[186:187], v[104:105], v[134:135] op_sel_hi:[1,0]
	v_pk_mul_f32 v[188:189], v[102:103], v[134:135] op_sel_hi:[1,0]
	v_pk_mul_f32 v[190:191], v[100:101], v[134:135] op_sel_hi:[1,0]
	v_pk_mul_f32 v[134:135], v[98:99], v[134:135] op_sel_hi:[1,0]
	v_lshl_add_u64 v[82:83], s[50:51], 0, v[82:83]
	v_pk_mul_f32 v[70:71], v[70:71], v[170:171] op_sel_hi:[1,0]
	v_pk_mul_f32 v[72:73], v[72:73], v[170:171] op_sel_hi:[1,0]
	v_lshl_add_u64 v[138:139], v[138:139], 0, v[164:165]
	v_lshl_add_u64 v[82:83], v[82:83], 0, v[164:165]
	v_pk_mul_f32 v[66:67], v[66:67], v[170:171] op_sel_hi:[1,0]
	v_pk_mul_f32 v[68:69], v[68:69], v[170:171] op_sel_hi:[1,0]
	v_pk_mul_f32 v[78:79], v[78:79], v[170:171] op_sel_hi:[1,0]
	v_pk_mul_f32 v[80:81], v[80:81], v[170:171] op_sel_hi:[1,0]
	v_pk_mul_f32 v[74:75], v[74:75], v[170:171] op_sel_hi:[1,0]
	v_pk_mul_f32 v[76:77], v[76:77], v[170:171] op_sel_hi:[1,0]
	s_waitcnt vmcnt(3)
	v_pk_mul_f32 v[84:85], v[212:213], v[126:127]
	v_pk_mul_f32 v[86:87], v[214:215], v[128:129]
	s_waitcnt vmcnt(2)
	v_pk_mul_f32 v[88:89], v[208:209], v[122:123]
	v_pk_mul_f32 v[90:91], v[210:211], v[124:125]
	s_waitcnt vmcnt(1)
	v_pk_mul_f32 v[92:93], v[204:205], v[118:119]
	v_pk_mul_f32 v[94:95], v[206:207], v[120:121]
	s_waitcnt vmcnt(0)
	v_pk_mul_f32 v[96:97], v[200:201], v[114:115]
	v_pk_mul_f32 v[98:99], v[202:203], v[116:117]
	v_pk_mul_f32 v[100:101], v[212:213], v[110:111]
	v_pk_mul_f32 v[102:103], v[214:215], v[112:113]
	v_pk_mul_f32 v[104:105], v[208:209], v[106:107]
	v_pk_mul_f32 v[106:107], v[210:211], v[108:109]
	v_pk_mul_f32 v[108:109], v[204:205], v[188:189]
	v_pk_mul_f32 v[110:111], v[206:207], v[186:187]
	v_pk_mul_f32 v[112:113], v[200:201], v[134:135]
	v_pk_mul_f32 v[114:115], v[202:203], v[190:191]
	v_pk_mul_f32 v[116:117], v[212:213], v[140:141]
	v_pk_mul_f32 v[118:119], v[214:215], v[136:137]
	v_pk_mul_f32 v[120:121], v[208:209], v[176:177]
	v_pk_mul_f32 v[122:123], v[210:211], v[168:169]
	v_pk_mul_f32 v[124:125], v[204:205], v[180:181]
	v_pk_mul_f32 v[126:127], v[206:207], v[178:179]
	v_pk_mul_f32 v[134:135], v[200:201], v[184:185]
	v_pk_mul_f32 v[136:137], v[202:203], v[182:183]
	global_store_dwordx4 v[172:173], v[84:87], off
	global_store_dwordx4 v[172:173], v[88:91], off offset:16
	global_store_dwordx4 v[172:173], v[92:95], off offset:512
	global_store_dwordx4 v[172:173], v[96:99], off offset:528
	global_store_dwordx4 v[174:175], v[100:103], off
	global_store_dwordx4 v[174:175], v[104:107], off offset:16
	global_store_dwordx4 v[174:175], v[108:111], off offset:512
	global_store_dwordx4 v[174:175], v[112:115], off offset:528
	global_store_dwordx4 v[138:139], v[116:119], off
	global_store_dwordx4 v[138:139], v[120:123], off offset:16
	global_store_dwordx4 v[138:139], v[124:127], off offset:512
	global_store_dwordx4 v[138:139], v[134:137], off offset:528
	v_pk_mul_f32 v[72:73], v[206:207], v[72:73]
	v_pk_mul_f32 v[70:71], v[204:205], v[70:71]
	global_store_dwordx4 v[82:83], v[70:73], off offset:512
	ds_read2_b32 v[70:71], v167 offset0:128 offset1:144
	v_pk_mul_f32 v[68:69], v[202:203], v[68:69]
	v_pk_mul_f32 v[66:67], v[200:201], v[66:67]
	global_store_dwordx4 v[82:83], v[66:69], off offset:528
	v_pk_mul_f32 v[78:79], v[212:213], v[78:79]
	s_waitcnt lgkmcnt(0)
;     __device__ __forceinline__ void fused(Acc& acc, const Unit& u, int wr, int wc, int fr, int fq, LAS unsigned char* lds) const {
;     ...
; #pragma unroll
;         for (int ai = 0; ai < 2; ++ai)
; #pragma unroll
;             for (int m = 0; m < 4; ++m) {
;                 const int rt = ai * HALF + wr * 64 + m * 16 + fr; const int row = u.pm * BM + rt; const float rs = S[rt];
; #pragma unroll
;                 for (int bj = 0; bj < 2; ++bj) {
;                     const int col = u.pn * BM + bj * HALF + wc * 32 + 8 * fq; const size_t off = (size_t)row * D + col;
;                     *(f32x4*)(out + off) = acc[ai][bj][m][0] * rs * gg[bj][0]; *(f32x4*)(out + off + 4) = acc[ai][bj][m][1] * rs * gg[bj][1];
;                 }
;             }
	v_pk_mul_f32 v[50:51], v[50:51], v[70:71] op_sel_hi:[1,0]
	v_lshlrev_b64 v[66:67], 12, v[142:143]
	v_lshl_add_u64 v[66:67], s[50:51], 0, v[66:67]
	v_pk_mul_f32 v[52:53], v[52:53], v[70:71] op_sel_hi:[1,0]
	v_lshl_add_u64 v[66:67], v[66:67], 0, v[164:165]
	v_pk_mul_f32 v[52:53], v[202:203], v[52:53]
	v_pk_mul_f32 v[50:51], v[200:201], v[50:51]
	global_store_dwordx4 v[66:67], v[50:53], off offset:528
	v_pk_mul_f32 v[62:63], v[62:63], v[70:71] op_sel_hi:[1,0]
	v_pk_mul_f32 v[64:65], v[64:65], v[70:71] op_sel_hi:[1,0]
	v_mov_b32_e32 v50, v71
	v_lshlrev_b64 v[52:53], 12, v[144:145]
	v_lshl_add_u64 v[52:53], s[50:51], 0, v[52:53]
	v_pk_mul_f32 v[38:39], v[38:39], v[50:51] op_sel_hi:[1,0]
	v_pk_mul_f32 v[40:41], v[40:41], v[50:51] op_sel_hi:[1,0]
	v_lshl_add_u64 v[52:53], v[52:53], 0, v[164:165]
	v_pk_mul_f32 v[40:41], v[206:207], v[40:41]
	v_pk_mul_f32 v[38:39], v[204:205], v[38:39]
	global_store_dwordx4 v[52:53], v[38:41], off offset:512
	ds_read2_b32 v[38:39], v167 offset0:160 offset1:176
	v_pk_mul_f32 v[34:35], v[34:35], v[50:51] op_sel_hi:[1,0]
	v_pk_mul_f32 v[36:37], v[36:37], v[50:51] op_sel_hi:[1,0]
	v_pk_mul_f32 v[34:35], v[200:201], v[34:35]
	v_pk_mul_f32 v[36:37], v[202:203], v[36:37]
	global_store_dwordx4 v[52:53], v[34:37], off offset:528
	s_waitcnt lgkmcnt(0)
	v_pk_mul_f32 v[18:19], v[18:19], v[38:39] op_sel_hi:[1,0]
	v_pk_mul_f32 v[20:21], v[20:21], v[38:39] op_sel_hi:[1,0]
	v_lshlrev_b64 v[34:35], 12, v[146:147]
	v_lshl_add_u64 v[34:35], s[50:51], 0, v[34:35]
	v_lshl_add_u64 v[34:35], v[34:35], 0, v[164:165]
	v_pk_mul_f32 v[20:21], v[202:203], v[20:21]
	v_pk_mul_f32 v[18:19], v[200:201], v[18:19]
	global_store_dwordx4 v[34:35], v[18:21], off offset:528
	v_pk_mul_f32 v[46:47], v[46:47], v[50:51] op_sel_hi:[1,0]
	v_pk_mul_f32 v[30:31], v[30:31], v[38:39] op_sel_hi:[1,0]
	v_mov_b32_e32 v18, v39
	v_pk_mul_f32 v[22:23], v[22:23], v[38:39] op_sel_hi:[1,0]
	v_pk_mul_f32 v[24:25], v[24:25], v[38:39] op_sel_hi:[1,0]
	v_pk_mul_f32 v[20:21], v[162:163], v[18:19] op_sel_hi:[1,0]
	v_pk_mul_f32 v[62:63], v[212:213], v[62:63]
	v_pk_mul_f32 v[46:47], v[212:213], v[46:47]
	v_pk_mul_f32 v[30:31], v[212:213], v[30:31]
	v_pk_mul_f32 v[24:25], v[206:207], v[24:25]
	v_pk_mul_f32 v[22:23], v[204:205], v[22:23]
	v_pk_mul_f32 v[212:213], v[212:213], v[20:21]
	v_lshlrev_b64 v[20:21], 12, v[148:149]
	v_pk_mul_f32 v[48:49], v[48:49], v[50:51] op_sel_hi:[1,0]
	v_pk_mul_f32 v[32:33], v[32:33], v[38:39] op_sel_hi:[1,0]
	global_store_dwordx4 v[34:35], v[22:25], off offset:512
	v_lshl_add_u64 v[20:21], s[50:51], 0, v[20:21]
	v_pk_mul_f32 v[80:81], v[214:215], v[80:81]
	v_pk_mul_f32 v[22:23], v[160:161], v[18:19] op_sel_hi:[1,0]
	v_pk_mul_f32 v[64:65], v[214:215], v[64:65]
	v_pk_mul_f32 v[48:49], v[214:215], v[48:49]
	v_pk_mul_f32 v[32:33], v[214:215], v[32:33]
	v_pk_mul_f32 v[214:215], v[214:215], v[22:23]
	v_lshl_add_u64 v[20:21], v[20:21], 0, v[164:165]
	global_store_dwordx4 v[82:83], v[78:81], off
	v_pk_mul_f32 v[58:59], v[58:59], v[70:71] op_sel_hi:[1,0]
	v_pk_mul_f32 v[60:61], v[60:61], v[70:71] op_sel_hi:[1,0]
	v_pk_mul_f32 v[42:43], v[42:43], v[50:51] op_sel_hi:[1,0]
	v_pk_mul_f32 v[44:45], v[44:45], v[50:51] op_sel_hi:[1,0]
	v_pk_mul_f32 v[26:27], v[26:27], v[38:39] op_sel_hi:[1,0]
	v_pk_mul_f32 v[28:29], v[28:29], v[38:39] op_sel_hi:[1,0]
	global_store_dwordx4 v[20:21], v[212:215], off
	v_pk_mul_f32 v[76:77], v[210:211], v[76:77]
	v_pk_mul_f32 v[74:75], v[208:209], v[74:75]
	v_pk_mul_f32 v[212:213], v[158:159], v[18:19] op_sel_hi:[1,0]
	v_pk_mul_f32 v[214:215], v[154:155], v[18:19] op_sel_hi:[1,0]
	v_pk_mul_f32 v[60:61], v[210:211], v[60:61]
	v_pk_mul_f32 v[58:59], v[208:209], v[58:59]
	v_pk_mul_f32 v[44:45], v[210:211], v[44:45]
	v_pk_mul_f32 v[42:43], v[208:209], v[42:43]
	v_pk_mul_f32 v[28:29], v[210:211], v[28:29]
	v_pk_mul_f32 v[26:27], v[208:209], v[26:27]
	v_pk_mul_f32 v[210:211], v[210:211], v[214:215]
	v_pk_mul_f32 v[208:209], v[208:209], v[212:213]
	global_store_dwordx4 v[82:83], v[74:77], off offset:16
	v_pk_mul_f32 v[54:55], v[54:55], v[70:71] op_sel_hi:[1,0]
	v_pk_mul_f32 v[56:57], v[56:57], v[70:71] op_sel_hi:[1,0]
	global_store_dwordx4 v[20:21], v[208:211], off offset:16
	v_pk_mul_f32 v[56:57], v[206:207], v[56:57]
	v_pk_mul_f32 v[54:55], v[204:205], v[54:55]
	v_pk_mul_f32 v[208:209], v[156:157], v[18:19] op_sel_hi:[1,0]
	v_pk_mul_f32 v[210:211], v[150:151], v[18:19] op_sel_hi:[1,0]
	v_pk_mul_f32 v[204:205], v[204:205], v[208:209]
	v_pk_mul_f32 v[206:207], v[206:207], v[210:211]
	global_store_dwordx4 v[20:21], v[204:207], off offset:512
	global_store_dwordx4 v[66:67], v[62:65], off
	global_store_dwordx4 v[66:67], v[58:61], off offset:16
	v_pk_mul_f32 v[204:205], v[152:153], v[18:19] op_sel_hi:[1,0]
	v_pk_mul_f32 v[206:207], v[132:133], v[18:19] op_sel_hi:[1,0]
	v_pk_mul_f32 v[200:201], v[200:201], v[204:205]
	v_pk_mul_f32 v[202:203], v[202:203], v[206:207]
	global_store_dwordx4 v[66:67], v[54:57], off offset:512
	global_store_dwordx4 v[52:53], v[46:49], off
	global_store_dwordx4 v[52:53], v[42:45], off offset:16
	global_store_dwordx4 v[34:35], v[30:33], off
	global_store_dwordx4 v[34:35], v[26:29], off offset:16
	global_store_dwordx4 v[20:21], v[200:203], off offset:528
